# P2a S3 epilogue: triangular masks by two compares per register (row offset vs lane column) instead of four v_readlane of stored lane masks
# baseline (speedup 1.0000x reference)
; #define LAS __attribute__((address_space(3)))
; #define MFMA32(a, b, c) __builtin_amdgcn_mfma_f32_32x32x16_bf16((a), (b), (c), 0, 0, 0)
; __device__ __forceinline__ void gdn_prep_phase(LAS unsigned char* lds, const GdnPrepArgs& A, int bid, int G, const unsigned char* zero_page) {
;     ...
;         const LAS unsigned char* ia = lds + (which ? L_QN : L_KN) + (32 * rt + r) * QS_ + 16 * hh;
;         const LAS unsigned char* ib = lds + L_KN + (32 * ct + r) * QS_ + 16 * hh;
;         f32x16 acc = zero16();
; #pragma unroll
;         for (int ks = 0; ks < 8; ++ks) acc = MFMA32(*(const LAS bf16x8*)(ia + 32 * ks), *(const LAS bf16x8*)(ib + 32 * ks), acc);
;         const LAS float* sc = (const LAS float*)(lds + L_SC);
;         const int j = 32 * ct + r; const float gfj = sc[j], gbj = sc[64 + j];
; #pragma unroll
;         for (int reg = 0; reg < 16; ++reg) {
;             const int i = 32 * rt + (reg & 3) + 8 * (reg >> 2) + 4 * hh; const float val = acc[reg];
;             const float ef = __expf(sc[i] - gfj), eb = __expf(sc[64 + i] - gbj);
.LBB0_209:
	s_mov_b32 s98, 0x3fb8aa3b
	ds_read2st64_b32 v[216:217], v55 offset1:1
	ds_read2st64_b32 v[136:137], v72 offset1:1
	ds_read2st64_b32 v[138:139], v74 offset1:1
	ds_read2st64_b32 v[140:141], v76 offset1:1
	ds_read2st64_b32 v[142:143], v78 offset1:1
	ds_read2st64_b32 v[144:145], v80 offset1:1
	ds_read2st64_b32 v[146:147], v82 offset1:1
	ds_read2st64_b32 v[148:149], v84 offset1:1
	ds_read2st64_b32 v[150:151], v86 offset1:1
	ds_read2st64_b32 v[152:153], v88 offset1:1
	ds_read2st64_b32 v[154:155], v90 offset1:1
	ds_read2st64_b32 v[156:157], v92 offset1:1
	ds_read2st64_b32 v[158:159], v94 offset1:1
	ds_read2st64_b32 v[160:161], v96 offset1:1
	ds_read2st64_b32 v[162:163], v98 offset1:1
	ds_read2st64_b32 v[174:175], v100 offset1:1
	ds_read2st64_b32 v[176:177], v102 offset1:1
	ds_read2st64_b32 v[178:179], v72 offset0:2 offset1:3
	ds_read2st64_b32 v[180:181], v74 offset0:2 offset1:3
	ds_read2st64_b32 v[182:183], v76 offset0:2 offset1:3
	ds_read2st64_b32 v[230:231], v78 offset0:2 offset1:3
	ds_read2st64_b32 v[232:233], v80 offset0:2 offset1:3
	ds_read2st64_b32 v[234:235], v82 offset0:2 offset1:3
	ds_read2st64_b32 v[236:237], v84 offset0:2 offset1:3
	ds_read2st64_b32 v[238:239], v86 offset0:2 offset1:3
	ds_read2st64_b32 v[240:241], v88 offset0:2 offset1:3
	ds_read2st64_b32 v[242:243], v90 offset0:2 offset1:3
	ds_read2st64_b32 v[244:245], v92 offset0:2 offset1:3
	ds_read2st64_b32 v[248:249], v94 offset0:2 offset1:3
	ds_read2st64_b32 v[208:209], v96 offset0:2 offset1:3
	ds_read2st64_b32 v[210:211], v98 offset0:2 offset1:3
	ds_read2st64_b32 v[212:213], v100 offset0:2 offset1:3
	ds_read2st64_b32 v[214:215], v102 offset0:2 offset1:3
	ds_read_b128 v[32:35], v190
	ds_read_b128 v[36:39], v191
	s_waitcnt lgkmcnt(0)
	v_mfma_f32_32x32x16_bf16 v[2:17], v[32:35], v[36:39], 0
	v_pk_add_f32 v[136:137], v[136:137], v[216:217] neg_lo:[0,1] neg_hi:[0,1]
	v_pk_add_f32 v[138:139], v[138:139], v[216:217] neg_lo:[0,1] neg_hi:[0,1]
	v_pk_mul_f32 v[136:137], v[136:137], s[98:99] op_sel_hi:[1,0]
	v_pk_mul_f32 v[138:139], v[138:139], s[98:99] op_sel_hi:[1,0]
	v_exp_f32_e32 v136, v136
	v_exp_f32_e32 v137, v137
	v_exp_f32_e32 v138, v138
	v_exp_f32_e32 v139, v139
	ds_read_b128 v[32:35], v190 offset:32
	ds_read_b128 v[36:39], v191 offset:32
	s_waitcnt lgkmcnt(0)
	v_mfma_f32_32x32x16_bf16 v[2:17], v[32:35], v[36:39], v[2:17]
	v_pk_add_f32 v[140:141], v[140:141], v[216:217] neg_lo:[0,1] neg_hi:[0,1]
	v_pk_add_f32 v[142:143], v[142:143], v[216:217] neg_lo:[0,1] neg_hi:[0,1]
	v_pk_mul_f32 v[140:141], v[140:141], s[98:99] op_sel_hi:[1,0]
	v_pk_mul_f32 v[142:143], v[142:143], s[98:99] op_sel_hi:[1,0]
	v_exp_f32_e32 v140, v140
	v_exp_f32_e32 v141, v141
	v_exp_f32_e32 v142, v142
	v_exp_f32_e32 v143, v143
	ds_read_b128 v[32:35], v190 offset:64
	ds_read_b128 v[36:39], v191 offset:64
	s_waitcnt lgkmcnt(0)
	v_mfma_f32_32x32x16_bf16 v[2:17], v[32:35], v[36:39], v[2:17]
	v_pk_add_f32 v[144:145], v[144:145], v[216:217] neg_lo:[0,1] neg_hi:[0,1]
	v_pk_add_f32 v[146:147], v[146:147], v[216:217] neg_lo:[0,1] neg_hi:[0,1]
	v_pk_mul_f32 v[144:145], v[144:145], s[98:99] op_sel_hi:[1,0]
	v_pk_mul_f32 v[146:147], v[146:147], s[98:99] op_sel_hi:[1,0]
	v_exp_f32_e32 v144, v144
	v_exp_f32_e32 v145, v145
	v_exp_f32_e32 v146, v146
	v_exp_f32_e32 v147, v147
	ds_read_b128 v[32:35], v190 offset:96
	ds_read_b128 v[36:39], v191 offset:96
	s_waitcnt lgkmcnt(0)
	v_mfma_f32_32x32x16_bf16 v[2:17], v[32:35], v[36:39], v[2:17]
	v_pk_add_f32 v[148:149], v[148:149], v[216:217] neg_lo:[0,1] neg_hi:[0,1]
	v_pk_add_f32 v[150:151], v[150:151], v[216:217] neg_lo:[0,1] neg_hi:[0,1]
	v_pk_mul_f32 v[148:149], v[148:149], s[98:99] op_sel_hi:[1,0]
	v_pk_mul_f32 v[150:151], v[150:151], s[98:99] op_sel_hi:[1,0]
	v_exp_f32_e32 v148, v148
	v_exp_f32_e32 v149, v149
	v_exp_f32_e32 v150, v150
	v_exp_f32_e32 v151, v151
	ds_read_b128 v[32:35], v190 offset:128
	ds_read_b128 v[36:39], v191 offset:128
	s_waitcnt lgkmcnt(0)
	v_mfma_f32_32x32x16_bf16 v[2:17], v[32:35], v[36:39], v[2:17]
	v_pk_add_f32 v[152:153], v[152:153], v[216:217] neg_lo:[0,1] neg_hi:[0,1]
	v_pk_add_f32 v[154:155], v[154:155], v[216:217] neg_lo:[0,1] neg_hi:[0,1]
	v_pk_mul_f32 v[152:153], v[152:153], s[98:99] op_sel_hi:[1,0]
	v_pk_mul_f32 v[154:155], v[154:155], s[98:99] op_sel_hi:[1,0]
	v_exp_f32_e32 v152, v152
	v_exp_f32_e32 v153, v153
	v_exp_f32_e32 v154, v154
	v_exp_f32_e32 v155, v155
	ds_read_b128 v[32:35], v190 offset:160
	ds_read_b128 v[36:39], v191 offset:160
	s_waitcnt lgkmcnt(0)
	v_mfma_f32_32x32x16_bf16 v[2:17], v[32:35], v[36:39], v[2:17]
	v_pk_add_f32 v[156:157], v[156:157], v[216:217] neg_lo:[0,1] neg_hi:[0,1]
	v_pk_add_f32 v[158:159], v[158:159], v[216:217] neg_lo:[0,1] neg_hi:[0,1]
	v_pk_mul_f32 v[156:157], v[156:157], s[98:99] op_sel_hi:[1,0]
	v_pk_mul_f32 v[158:159], v[158:159], s[98:99] op_sel_hi:[1,0]
	v_exp_f32_e32 v156, v156
	v_exp_f32_e32 v157, v157
	v_exp_f32_e32 v158, v158
	v_exp_f32_e32 v159, v159
	ds_read_b128 v[32:35], v190 offset:192
	ds_read_b128 v[36:39], v191 offset:192
	s_waitcnt lgkmcnt(0)
	v_mfma_f32_32x32x16_bf16 v[2:17], v[32:35], v[36:39], v[2:17]
	v_pk_add_f32 v[160:161], v[160:161], v[216:217] neg_lo:[0,1] neg_hi:[0,1]
	v_pk_add_f32 v[162:163], v[162:163], v[216:217] neg_lo:[0,1] neg_hi:[0,1]
	v_pk_mul_f32 v[160:161], v[160:161], s[98:99] op_sel_hi:[1,0]
	v_pk_mul_f32 v[162:163], v[162:163], s[98:99] op_sel_hi:[1,0]
	v_exp_f32_e32 v160, v160
	v_exp_f32_e32 v161, v161
	v_exp_f32_e32 v162, v162
	v_exp_f32_e32 v163, v163
	ds_read_b128 v[32:35], v190 offset:224
	ds_read_b128 v[36:39], v191 offset:224
	s_waitcnt lgkmcnt(0)
	v_mfma_f32_32x32x16_bf16 v[2:17], v[32:35], v[36:39], v[2:17]
	v_pk_add_f32 v[174:175], v[174:175], v[216:217] neg_lo:[0,1] neg_hi:[0,1]
	v_pk_add_f32 v[176:177], v[176:177], v[216:217] neg_lo:[0,1] neg_hi:[0,1]
	v_pk_mul_f32 v[174:175], v[174:175], s[98:99] op_sel_hi:[1,0]
	v_pk_mul_f32 v[176:177], v[176:177], s[98:99] op_sel_hi:[1,0]
	v_exp_f32_e32 v174, v174
	v_exp_f32_e32 v175, v175
	v_exp_f32_e32 v176, v176
	v_exp_f32_e32 v177, v177
	v_mbcnt_lo_u32_b32 v222, -1, 0
	v_mbcnt_hi_u32_b32 v222, -1, v222
	v_readfirstlane_b32 s99, v0
	v_and_b32_e32 v223, 31, v222
	v_lshrrev_b32_e32 v222, 5, v222
	s_lshr_b32 s99, s99, 6
	s_and_b32 s46, s99, 1
	s_bfe_u32 s47, s99, 0x10001
	s_sub_i32 s46, s46, s47
	s_lshl_b32 s46, s46, 5
	v_lshlrev_b32_e32 v222, 2, v222
	v_sub_u32_e32 v222, v223, v222
	v_add_u32_e32 v222, s46, v222
	s_and_b64 vcc, exec, s[4:5]
	s_cbranch_vccz .Ls3_lpath
; #define LAS __attribute__((address_space(3)))
; __device__ __forceinline__ unsigned pkbf(float a, float b) { bf16x2_t v = __builtin_convertvector((f32x2_t){a, b}, bf16x2_t); return __builtin_bit_cast(unsigned, v); }
; __device__ __forceinline__ void gdn_prep_phase(LAS unsigned char* lds, const GdnPrepArgs& A, int bid, int G, const unsigned char* zero_page) {
;     ...
;             if (which == 0) {
;                 const float lf = (i > j) ? sc[128 + i] * val * ef : 0.f, lb = (i < j) ? sc[192 + i] * val * eb : 0.f;
;                 ((LAS float*)(lds + L_LPF))[i * 64 + (j & 3) * 16 + (j >> 2)] = lf;
;                 const int i2 = 63 - i, j2 = 63 - j;
;                 ((LAS float*)(lds + L_LPB))[i2 * 64 + (j2 & 3) * 16 + (j2 >> 2)] = lb;
;             } else {
;                 const float af = (i >= j) ? QSCALE * val * ef : 0.f, ab = (i <= j) ? QSCALE * val * eb : 0.f;
;                 *(LAS unsigned short*)(lds + L_AF + i * AS_ + j * 2) = (unsigned short)(pkbf(af, 0.f) & 0xffffu);
;                 *(LAS unsigned short*)(lds + L_AB + i * AS_ + j * 2) = (unsigned short)(pkbf(ab, 0.f) & 0xffffu);
	v_cmp_ge_i32_e64 s[46:47], 0, v222
	v_cmp_le_i32_e64 s[48:49], 0, v222
	v_mul_f32_e32 v218, 0x3db504f3, v2
	v_pk_mul_f32 v[220:221], v[136:137], v[218:219] op_sel_hi:[1,0]
	s_nop 0
	v_cndmask_b32_e64 v220, 0, v220, s[46:47]
	v_cndmask_b32_e64 v221, 0, v221, s[48:49]
	v_cvt_pk_bf16_f32 v220, v220, v221
	ds_write_b16 v228, v220
	ds_write_b16_d16_hi v229, v220
	v_cmp_ge_i32_e64 s[46:47], 1, v222
	v_cmp_le_i32_e64 s[48:49], 1, v222
	v_mul_f32_e32 v218, 0x3db504f3, v3
	v_pk_mul_f32 v[220:221], v[138:139], v[218:219] op_sel_hi:[1,0]
	s_nop 0
	v_cndmask_b32_e64 v220, 0, v220, s[46:47]
	v_cndmask_b32_e64 v221, 0, v221, s[48:49]
	v_cvt_pk_bf16_f32 v220, v220, v221
	ds_write_b16 v228, v220 offset:144
	ds_write_b16_d16_hi v229, v220 offset:144
	v_cmp_ge_i32_e64 s[46:47], 2, v222
	v_cmp_le_i32_e64 s[48:49], 2, v222
	v_mul_f32_e32 v218, 0x3db504f3, v4
	v_pk_mul_f32 v[220:221], v[140:141], v[218:219] op_sel_hi:[1,0]
	s_nop 0
	v_cndmask_b32_e64 v220, 0, v220, s[46:47]
	v_cndmask_b32_e64 v221, 0, v221, s[48:49]
	v_cvt_pk_bf16_f32 v220, v220, v221
	ds_write_b16 v228, v220 offset:288
	ds_write_b16_d16_hi v229, v220 offset:288
	v_cmp_ge_i32_e64 s[46:47], 3, v222
	v_cmp_le_i32_e64 s[48:49], 3, v222
	v_mul_f32_e32 v218, 0x3db504f3, v5
	v_pk_mul_f32 v[220:221], v[142:143], v[218:219] op_sel_hi:[1,0]
	s_nop 0
	v_cndmask_b32_e64 v220, 0, v220, s[46:47]
	v_cndmask_b32_e64 v221, 0, v221, s[48:49]
	v_cvt_pk_bf16_f32 v220, v220, v221
	ds_write_b16 v228, v220 offset:432
	ds_write_b16_d16_hi v229, v220 offset:432
	v_cmp_ge_i32_e64 s[46:47], 8, v222
	v_cmp_le_i32_e64 s[48:49], 8, v222
	v_mul_f32_e32 v218, 0x3db504f3, v6
	v_pk_mul_f32 v[220:221], v[144:145], v[218:219] op_sel_hi:[1,0]
	s_nop 0
	v_cndmask_b32_e64 v220, 0, v220, s[46:47]
	v_cndmask_b32_e64 v221, 0, v221, s[48:49]
	v_cvt_pk_bf16_f32 v220, v220, v221
	ds_write_b16 v228, v220 offset:1152
	ds_write_b16_d16_hi v229, v220 offset:1152
	v_cmp_ge_i32_e64 s[46:47], 9, v222
	v_cmp_le_i32_e64 s[48:49], 9, v222
	v_mul_f32_e32 v218, 0x3db504f3, v7
	v_pk_mul_f32 v[220:221], v[146:147], v[218:219] op_sel_hi:[1,0]
	s_nop 0
	v_cndmask_b32_e64 v220, 0, v220, s[46:47]
	v_cndmask_b32_e64 v221, 0, v221, s[48:49]
	v_cvt_pk_bf16_f32 v220, v220, v221
	ds_write_b16 v228, v220 offset:1296
	ds_write_b16_d16_hi v229, v220 offset:1296
	v_cmp_ge_i32_e64 s[46:47], 10, v222
	v_cmp_le_i32_e64 s[48:49], 10, v222
	v_mul_f32_e32 v218, 0x3db504f3, v8
	v_pk_mul_f32 v[220:221], v[148:149], v[218:219] op_sel_hi:[1,0]
	s_nop 0
	v_cndmask_b32_e64 v220, 0, v220, s[46:47]
	v_cndmask_b32_e64 v221, 0, v221, s[48:49]
	v_cvt_pk_bf16_f32 v220, v220, v221
	ds_write_b16 v228, v220 offset:1440
	ds_write_b16_d16_hi v229, v220 offset:1440
	v_cmp_ge_i32_e64 s[46:47], 11, v222
	v_cmp_le_i32_e64 s[48:49], 11, v222
	v_mul_f32_e32 v218, 0x3db504f3, v9
	v_pk_mul_f32 v[220:221], v[150:151], v[218:219] op_sel_hi:[1,0]
	s_nop 0
	v_cndmask_b32_e64 v220, 0, v220, s[46:47]
	v_cndmask_b32_e64 v221, 0, v221, s[48:49]
	v_cvt_pk_bf16_f32 v220, v220, v221
	ds_write_b16 v228, v220 offset:1584
	ds_write_b16_d16_hi v229, v220 offset:1584
	v_cmp_ge_i32_e64 s[46:47], 16, v222
	v_cmp_le_i32_e64 s[48:49], 16, v222
	v_mul_f32_e32 v218, 0x3db504f3, v10
	v_pk_mul_f32 v[220:221], v[152:153], v[218:219] op_sel_hi:[1,0]
	s_nop 0
	v_cndmask_b32_e64 v220, 0, v220, s[46:47]
	v_cndmask_b32_e64 v221, 0, v221, s[48:49]
	v_cvt_pk_bf16_f32 v220, v220, v221
	ds_write_b16 v228, v220 offset:2304
	ds_write_b16_d16_hi v229, v220 offset:2304
	v_cmp_ge_i32_e64 s[46:47], 17, v222
	v_cmp_le_i32_e64 s[48:49], 17, v222
	v_mul_f32_e32 v218, 0x3db504f3, v11
	v_pk_mul_f32 v[220:221], v[154:155], v[218:219] op_sel_hi:[1,0]
	s_nop 0
	v_cndmask_b32_e64 v220, 0, v220, s[46:47]
	v_cndmask_b32_e64 v221, 0, v221, s[48:49]
	v_cvt_pk_bf16_f32 v220, v220, v221
	ds_write_b16 v228, v220 offset:2448
	ds_write_b16_d16_hi v229, v220 offset:2448
	v_cmp_ge_i32_e64 s[46:47], 18, v222
	v_cmp_le_i32_e64 s[48:49], 18, v222
	v_mul_f32_e32 v218, 0x3db504f3, v12
	v_pk_mul_f32 v[220:221], v[156:157], v[218:219] op_sel_hi:[1,0]
	s_nop 0
	v_cndmask_b32_e64 v220, 0, v220, s[46:47]
	v_cndmask_b32_e64 v221, 0, v221, s[48:49]
	v_cvt_pk_bf16_f32 v220, v220, v221
	ds_write_b16 v228, v220 offset:2592
	ds_write_b16_d16_hi v229, v220 offset:2592
	v_cmp_ge_i32_e64 s[46:47], 19, v222
	v_cmp_le_i32_e64 s[48:49], 19, v222
	v_mul_f32_e32 v218, 0x3db504f3, v13
	v_pk_mul_f32 v[220:221], v[158:159], v[218:219] op_sel_hi:[1,0]
	s_nop 0
	v_cndmask_b32_e64 v220, 0, v220, s[46:47]
	v_cndmask_b32_e64 v221, 0, v221, s[48:49]
	v_cvt_pk_bf16_f32 v220, v220, v221
	ds_write_b16 v228, v220 offset:2736
	ds_write_b16_d16_hi v229, v220 offset:2736
	v_cmp_ge_i32_e64 s[46:47], 24, v222
	v_cmp_le_i32_e64 s[48:49], 24, v222
	v_mul_f32_e32 v218, 0x3db504f3, v14
	v_pk_mul_f32 v[220:221], v[160:161], v[218:219] op_sel_hi:[1,0]
	s_nop 0
	v_cndmask_b32_e64 v220, 0, v220, s[46:47]
	v_cndmask_b32_e64 v221, 0, v221, s[48:49]
	v_cvt_pk_bf16_f32 v220, v220, v221
	ds_write_b16 v228, v220 offset:3456
	ds_write_b16_d16_hi v229, v220 offset:3456
	v_cmp_ge_i32_e64 s[46:47], 25, v222
	v_cmp_le_i32_e64 s[48:49], 25, v222
	v_mul_f32_e32 v218, 0x3db504f3, v15
	v_pk_mul_f32 v[220:221], v[162:163], v[218:219] op_sel_hi:[1,0]
	s_nop 0
	v_cndmask_b32_e64 v220, 0, v220, s[46:47]
	v_cndmask_b32_e64 v221, 0, v221, s[48:49]
	v_cvt_pk_bf16_f32 v220, v220, v221
	ds_write_b16 v228, v220 offset:3600
	ds_write_b16_d16_hi v229, v220 offset:3600
	v_cmp_ge_i32_e64 s[46:47], 26, v222
	v_cmp_le_i32_e64 s[48:49], 26, v222
	v_mul_f32_e32 v218, 0x3db504f3, v16
	v_pk_mul_f32 v[220:221], v[174:175], v[218:219] op_sel_hi:[1,0]
	s_nop 0
	v_cndmask_b32_e64 v220, 0, v220, s[46:47]
	v_cndmask_b32_e64 v221, 0, v221, s[48:49]
	v_cvt_pk_bf16_f32 v220, v220, v221
	ds_write_b16 v228, v220 offset:3744
	ds_write_b16_d16_hi v229, v220 offset:3744
	v_cmp_ge_i32_e64 s[46:47], 27, v222
	v_cmp_le_i32_e64 s[48:49], 27, v222
	v_mul_f32_e32 v218, 0x3db504f3, v17
	v_pk_mul_f32 v[220:221], v[176:177], v[218:219] op_sel_hi:[1,0]
	s_nop 0
	v_cndmask_b32_e64 v220, 0, v220, s[46:47]
	v_cndmask_b32_e64 v221, 0, v221, s[48:49]
	v_cvt_pk_bf16_f32 v220, v220, v221
	ds_write_b16 v228, v220 offset:3888
	ds_write_b16_d16_hi v229, v220 offset:3888
	s_branch .Ls3_done
; #define LAS __attribute__((address_space(3)))
; __device__ __forceinline__ void gdn_prep_phase(LAS unsigned char* lds, const GdnPrepArgs& A, int bid, int G, const unsigned char* zero_page) {
;     ...
;             if (which == 0) {
;                 const float lf = (i > j) ? sc[128 + i] * val * ef : 0.f, lb = (i < j) ? sc[192 + i] * val * eb : 0.f;
;                 ((LAS float*)(lds + L_LPF))[i * 64 + (j & 3) * 16 + (j >> 2)] = lf;
;                 const int i2 = 63 - i, j2 = 63 - j;
;                 ((LAS float*)(lds + L_LPB))[i2 * 64 + (j2 & 3) * 16 + (j2 >> 2)] = lb;
.Ls3_lpath:
	v_cmp_gt_i32_e64 s[46:47], 0, v222
	v_cmp_lt_i32_e64 s[48:49], 0, v222
	v_pk_mul_f32 v[178:179], v[178:179], v[2:3] op_sel_hi:[1,0]
	s_nop 0
	v_pk_mul_f32 v[178:179], v[178:179], v[136:137]
	s_nop 0
	v_cndmask_b32_e64 v178, 0, v178, s[46:47]
	v_cndmask_b32_e64 v179, 0, v179, s[48:49]
	ds_write_b32 v192, v178
	ds_write_b32 v73, v179
	v_cmp_gt_i32_e64 s[46:47], 1, v222
	v_cmp_lt_i32_e64 s[48:49], 1, v222
	v_pk_mul_f32 v[180:181], v[180:181], v[2:3] op_sel:[0,1] op_sel_hi:[1,1]
	s_nop 0
	v_pk_mul_f32 v[180:181], v[180:181], v[138:139]
	s_nop 0
	v_cndmask_b32_e64 v180, 0, v180, s[46:47]
	v_cndmask_b32_e64 v181, 0, v181, s[48:49]
	ds_write_b32 v193, v180
	ds_write_b32 v75, v181
	v_cmp_gt_i32_e64 s[46:47], 2, v222
	v_cmp_lt_i32_e64 s[48:49], 2, v222
	v_pk_mul_f32 v[182:183], v[182:183], v[4:5] op_sel_hi:[1,0]
	s_nop 0
	v_pk_mul_f32 v[182:183], v[182:183], v[140:141]
	s_nop 0
	v_cndmask_b32_e64 v182, 0, v182, s[46:47]
	v_cndmask_b32_e64 v183, 0, v183, s[48:49]
	ds_write_b32 v194, v182
	ds_write_b32 v77, v183
	v_cmp_gt_i32_e64 s[46:47], 3, v222
	v_cmp_lt_i32_e64 s[48:49], 3, v222
	v_pk_mul_f32 v[230:231], v[230:231], v[4:5] op_sel:[0,1] op_sel_hi:[1,1]
	s_nop 0
	v_pk_mul_f32 v[230:231], v[230:231], v[142:143]
	s_nop 0
	v_cndmask_b32_e64 v230, 0, v230, s[46:47]
	v_cndmask_b32_e64 v231, 0, v231, s[48:49]
	ds_write_b32 v195, v230
	ds_write_b32 v79, v231
	v_cmp_gt_i32_e64 s[46:47], 8, v222
	v_cmp_lt_i32_e64 s[48:49], 8, v222
	v_pk_mul_f32 v[232:233], v[232:233], v[6:7] op_sel_hi:[1,0]
	s_nop 0
	v_pk_mul_f32 v[232:233], v[232:233], v[144:145]
	s_nop 0
	v_cndmask_b32_e64 v232, 0, v232, s[46:47]
	v_cndmask_b32_e64 v233, 0, v233, s[48:49]
	ds_write_b32 v196, v232
	ds_write_b32 v81, v233
	v_cmp_gt_i32_e64 s[46:47], 9, v222
	v_cmp_lt_i32_e64 s[48:49], 9, v222
	v_pk_mul_f32 v[234:235], v[234:235], v[6:7] op_sel:[0,1] op_sel_hi:[1,1]
	s_nop 0
	v_pk_mul_f32 v[234:235], v[234:235], v[146:147]
	s_nop 0
	v_cndmask_b32_e64 v234, 0, v234, s[46:47]
	v_cndmask_b32_e64 v235, 0, v235, s[48:49]
	ds_write_b32 v197, v234
	ds_write_b32 v83, v235
	v_cmp_gt_i32_e64 s[46:47], 10, v222
	v_cmp_lt_i32_e64 s[48:49], 10, v222
	v_pk_mul_f32 v[236:237], v[236:237], v[8:9] op_sel_hi:[1,0]
	s_nop 0
	v_pk_mul_f32 v[236:237], v[236:237], v[148:149]
	s_nop 0
	v_cndmask_b32_e64 v236, 0, v236, s[46:47]
	v_cndmask_b32_e64 v237, 0, v237, s[48:49]
	ds_write_b32 v198, v236
	ds_write_b32 v85, v237
	v_cmp_gt_i32_e64 s[46:47], 11, v222
	v_cmp_lt_i32_e64 s[48:49], 11, v222
	v_pk_mul_f32 v[238:239], v[238:239], v[8:9] op_sel:[0,1] op_sel_hi:[1,1]
	s_nop 0
	v_pk_mul_f32 v[238:239], v[238:239], v[150:151]
	s_nop 0
	v_cndmask_b32_e64 v238, 0, v238, s[46:47]
	v_cndmask_b32_e64 v239, 0, v239, s[48:49]
	ds_write_b32 v199, v238
	ds_write_b32 v87, v239
	v_cmp_gt_i32_e64 s[46:47], 16, v222
	v_cmp_lt_i32_e64 s[48:49], 16, v222
	v_pk_mul_f32 v[240:241], v[240:241], v[10:11] op_sel_hi:[1,0]
	s_nop 0
	v_pk_mul_f32 v[240:241], v[240:241], v[152:153]
	s_nop 0
	v_cndmask_b32_e64 v240, 0, v240, s[46:47]
	v_cndmask_b32_e64 v241, 0, v241, s[48:49]
	ds_write_b32 v200, v240
	ds_write_b32 v89, v241
	v_cmp_gt_i32_e64 s[46:47], 17, v222
	v_cmp_lt_i32_e64 s[48:49], 17, v222
	v_pk_mul_f32 v[242:243], v[242:243], v[10:11] op_sel:[0,1] op_sel_hi:[1,1]
	s_nop 0
	v_pk_mul_f32 v[242:243], v[242:243], v[154:155]
	s_nop 0
	v_cndmask_b32_e64 v242, 0, v242, s[46:47]
	v_cndmask_b32_e64 v243, 0, v243, s[48:49]
	ds_write_b32 v201, v242
	ds_write_b32 v91, v243
	v_cmp_gt_i32_e64 s[46:47], 18, v222
	v_cmp_lt_i32_e64 s[48:49], 18, v222
	v_pk_mul_f32 v[244:245], v[244:245], v[12:13] op_sel_hi:[1,0]
	s_nop 0
	v_pk_mul_f32 v[244:245], v[244:245], v[156:157]
	s_nop 0
	v_cndmask_b32_e64 v244, 0, v244, s[46:47]
	v_cndmask_b32_e64 v245, 0, v245, s[48:49]
	ds_write_b32 v202, v244
	ds_write_b32 v93, v245
	v_cmp_gt_i32_e64 s[46:47], 19, v222
	v_cmp_lt_i32_e64 s[48:49], 19, v222
	v_pk_mul_f32 v[248:249], v[248:249], v[12:13] op_sel:[0,1] op_sel_hi:[1,1]
	s_nop 0
	v_pk_mul_f32 v[248:249], v[248:249], v[158:159]
	s_nop 0
	v_cndmask_b32_e64 v248, 0, v248, s[46:47]
	v_cndmask_b32_e64 v249, 0, v249, s[48:49]
	ds_write_b32 v203, v248
	ds_write_b32 v95, v249
	v_cmp_gt_i32_e64 s[46:47], 24, v222
	v_cmp_lt_i32_e64 s[48:49], 24, v222
	v_pk_mul_f32 v[208:209], v[208:209], v[14:15] op_sel_hi:[1,0]
	s_nop 0
	v_pk_mul_f32 v[208:209], v[208:209], v[160:161]
	s_nop 0
	v_cndmask_b32_e64 v208, 0, v208, s[46:47]
	v_cndmask_b32_e64 v209, 0, v209, s[48:49]
	ds_write_b32 v204, v208
	ds_write_b32 v97, v209
	v_cmp_gt_i32_e64 s[46:47], 25, v222
	v_cmp_lt_i32_e64 s[48:49], 25, v222
	v_pk_mul_f32 v[210:211], v[210:211], v[14:15] op_sel:[0,1] op_sel_hi:[1,1]
	s_nop 0
	v_pk_mul_f32 v[210:211], v[210:211], v[162:163]
	s_nop 0
	v_cndmask_b32_e64 v210, 0, v210, s[46:47]
	v_cndmask_b32_e64 v211, 0, v211, s[48:49]
	ds_write_b32 v205, v210
	ds_write_b32 v99, v211
	v_cmp_gt_i32_e64 s[46:47], 26, v222
	v_cmp_lt_i32_e64 s[48:49], 26, v222
	v_pk_mul_f32 v[212:213], v[212:213], v[16:17] op_sel_hi:[1,0]
	s_nop 0
	v_pk_mul_f32 v[212:213], v[212:213], v[174:175]
	s_nop 0
	v_cndmask_b32_e64 v212, 0, v212, s[46:47]
	v_cndmask_b32_e64 v213, 0, v213, s[48:49]
	ds_write_b32 v206, v212
	ds_write_b32 v101, v213
	v_cmp_gt_i32_e64 s[46:47], 27, v222
	v_cmp_lt_i32_e64 s[48:49], 27, v222
	v_pk_mul_f32 v[214:215], v[214:215], v[16:17] op_sel:[0,1] op_sel_hi:[1,1]
	s_nop 0
	v_pk_mul_f32 v[214:215], v[214:215], v[176:177]
	s_nop 0
	v_cndmask_b32_e64 v214, 0, v214, s[46:47]
	v_cndmask_b32_e64 v215, 0, v215, s[48:49]
	ds_write_b32 v207, v214
	ds_write_b32 v103, v215
